# attention inner loop rewritten by hand: 3-stage software pipeline (QK next / exp cur / PV prev), 3-deep LDS ring, pk_add row sums
# speedup vs baseline: 1.3041x; 1.3041x over previous
.LBB0_605:
	s_lshl_b32 s0, s9, 5
	s_and_b32 s0, s0, 0xe0
	s_ashr_i32 s1, s9, 3
	s_add_i32 s2, s0, s1
	s_and_b64 s[0:1], s[72:73], exec
	s_cselect_b32 s0, s2, s9
	v_mov_b32_e32 v4, v206
	s_ashr_i32 s19, s0, 7
	ds_read_b64 v[0:1], v129 offset:232
	s_lshl_b32 s1, s0, 8
	s_bfe_u32 s18, s0, 0x20005
	s_lshl_b32 s2, s19, 2
	s_and_b32 s1, s1, 0x1f00
	v_and_b32_e32 v5, 31, v4
	s_or_b32 s0, s18, s2
	v_ashrrev_i32_e32 v2, 1, v4
	s_lshl_b32 s20, s0, 1
	v_and_b32_e32 v2, 0xffffffe0, v2
	v_or_b32_e32 v3, s1, v5
	v_bfe_u32 v6, v4, 5, 1
	s_mul_i32 s16, s0, 0x108000
	s_mul_hi_i32 s17, s20, 0x84000
	v_add_u32_e32 v156, v3, v2
	s_waitcnt lgkmcnt(0)
	v_lshl_add_u64 v[8:9], v[0:1], 0, s[16:17]
	v_ashrrev_i32_e32 v157, 31, v156
	v_lshlrev_b32_e32 v128, 4, v6
	v_lshl_add_u64 v[2:3], v[8:9], 0, v[128:129]
	v_lshlrev_b64 v[10:11], 6, v[156:157]
	v_lshl_add_u64 v[2:3], v[2:3], 0, v[10:11]
	s_mov_b32 s1, 0x9ab5000
	v_add_co_u32_e32 v10, vcc, s1, v2
	s_add_i32 s2, s2, s8
	s_nop 0
	v_addc_co_u32_e32 v11, vcc, 0, v3, vcc
	global_load_dwordx4 v[130:133], v[10:11], off
	s_or_b32 s1, s2, s18
	s_mov_b64 s[4:5], 0x9ab5000
	s_lshl_b32 s2, s1, 1
	s_mov_b32 s1, 0x9b39000
	v_lshl_add_u64 v[10:11], v[2:3], 0, s[4:5]
	v_add_co_u32_e32 v2, vcc, s1, v2
	global_load_dwordx4 v[134:137], v[10:11], off offset:32
	s_nop 0
	v_addc_co_u32_e32 v3, vcc, 0, v3, vcc
	global_load_dwordx4 v[138:141], v[2:3], off
	global_load_dwordx4 v[142:145], v[2:3], off offset:32
	s_ashr_i32 s3, s2, 31
	s_lshl_b64 s[2:3], s[2:3], 2
	v_lshl_add_u64 v[10:11], v[0:1], 0, s[2:3]
	v_ashrrev_i32_e32 v20, 8, v4
	v_readfirstlane_b32 s2, v10
	v_readfirstlane_b32 s3, v11
	s_lshl_b32 s0, s0, 6
	v_bfe_u32 v21, v4, 2, 6
	v_mul_i32_i24_e32 v10, 0x2100, v20
	s_mul_hi_i32 s17, s0, 0x4200
	s_mov_b64 s[0:1], 0xab35000
	global_load_dwordx2 v[12:13], v213, s[2:3]
	v_lshlrev_b32_e32 v2, 4, v4
	v_mul_hi_i32_i24_e32 v3, 0x2100, v20
	v_and_b32_e32 v16, 48, v2
	v_and_b32_e32 v18, 0x70, v2
	v_or_b32_e32 v2, v10, v21
	v_lshl_add_u64 v[10:11], v[0:1], 0, s[16:17]
	v_ashrrev_i32_e32 v7, 3, v4
	v_lshlrev_b64 v[2:3], 6, v[2:3]
	v_lshl_add_u64 v[10:11], v[10:11], 0, s[0:1]
	v_mov_b32_e32 v17, v129
	v_lshl_add_u64 v[8:9], v[8:9], 0, v[2:3]
	v_mad_i64_i32 v[10:11], s[0:1], v7, s13, v[10:11]
	v_lshl_add_u64 v[8:9], v[8:9], 0, v[16:17]
	s_mov_b32 s0, 0xa2f5000
	v_add_co_u32_e32 v8, vcc, s0, v8
	v_mov_b32_e32 v19, v129
	s_nop 0
	v_addc_co_u32_e32 v9, vcc, 0, v9, vcc
	v_lshl_add_u64 v[10:11], v[10:11], 0, v[18:19]
	global_load_dwordx4 v[146:149], v[8:9], off
	global_load_dwordx4 v[150:153], v[10:11], off
	s_mov_b32 s0, 0xf800000
	s_movk_i32 s21, 0x50
	s_waitcnt vmcnt(6)
	v_and_b32_e32 v9, 0xffff0000, v130
	v_lshlrev_b32_e32 v8, 16, v130
	v_mul_f32_e32 v9, v9, v9
	v_lshlrev_b32_e32 v10, 16, v131
	v_fmac_f32_e32 v9, v8, v8
	v_and_b32_e32 v11, 0xffff0000, v131
	v_fmac_f32_e32 v9, v10, v10
	v_lshlrev_b32_e32 v14, 16, v132
	v_fmac_f32_e32 v9, v11, v11
	v_and_b32_e32 v15, 0xffff0000, v132
	v_fmac_f32_e32 v9, v14, v14
	v_lshlrev_b32_e32 v17, 16, v133
	v_fmac_f32_e32 v9, v15, v15
	v_and_b32_e32 v19, 0xffff0000, v133
	v_fmac_f32_e32 v9, v17, v17
	s_waitcnt vmcnt(5)
	v_lshlrev_b32_e32 v22, 16, v134
	v_fmac_f32_e32 v9, v19, v19
	s_waitcnt vmcnt(4)
	v_and_b32_e32 v11, 0xffff0000, v138
	v_and_b32_e32 v23, 0xffff0000, v134
	v_fmac_f32_e32 v9, v22, v22
	v_lshlrev_b32_e32 v10, 16, v138
	v_mul_f32_e32 v14, v11, v11
	v_lshlrev_b32_e32 v24, 16, v135
	v_fmac_f32_e32 v9, v23, v23
	v_fmac_f32_e32 v14, v10, v10
	v_lshlrev_b32_e32 v10, 16, v139
	v_and_b32_e32 v25, 0xffff0000, v135
	v_fmac_f32_e32 v9, v24, v24
	v_fmac_f32_e32 v14, v10, v10
	v_and_b32_e32 v10, 0xffff0000, v139
	v_lshlrev_b32_e32 v26, 16, v136
	v_fmac_f32_e32 v9, v25, v25
	v_fmac_f32_e32 v14, v10, v10
	v_lshlrev_b32_e32 v10, 16, v140
	v_and_b32_e32 v27, 0xffff0000, v136
	v_fmac_f32_e32 v9, v26, v26
	v_fmac_f32_e32 v14, v10, v10
	v_and_b32_e32 v10, 0xffff0000, v140
	v_lshlrev_b32_e32 v28, 16, v137
	v_fmac_f32_e32 v9, v27, v27
	v_fmac_f32_e32 v14, v10, v10
	v_lshlrev_b32_e32 v10, 16, v141
	v_and_b32_e32 v29, 0xffff0000, v137
	v_fmac_f32_e32 v9, v28, v28
	v_fmac_f32_e32 v14, v10, v10
	v_and_b32_e32 v10, 0xffff0000, v141
	v_fmac_f32_e32 v9, v29, v29
	v_fmac_f32_e32 v14, v10, v10
	s_waitcnt vmcnt(3)
	v_lshlrev_b32_e32 v10, 16, v142
	ds_bpermute_b32 v8, v194, v9
	v_fmac_f32_e32 v14, v10, v10
	v_and_b32_e32 v10, 0xffff0000, v142
	v_fmac_f32_e32 v14, v10, v10
	v_lshlrev_b32_e32 v10, 16, v143
	v_fmac_f32_e32 v14, v10, v10
	v_and_b32_e32 v10, 0xffff0000, v143
	v_fmac_f32_e32 v14, v10, v10
	v_lshlrev_b32_e32 v10, 16, v144
	v_fmac_f32_e32 v14, v10, v10
	v_and_b32_e32 v10, 0xffff0000, v144
	s_waitcnt lgkmcnt(0)
	v_add_f32_e32 v8, v9, v8
	v_fmac_f32_e32 v14, v10, v10
	v_lshlrev_b32_e32 v10, 16, v145
	s_waitcnt vmcnt(2)
	v_mul_f32_e32 v8, v12, v8
	v_fmac_f32_e32 v14, v10, v10
	v_and_b32_e32 v10, 0xffff0000, v145
	v_mul_f32_e32 v9, 0x4f800000, v8
	v_cmp_gt_f32_e32 vcc, s0, v8
	v_fmac_f32_e32 v14, v10, v10
	ds_bpermute_b32 v10, v194, v14
	v_cndmask_b32_e32 v8, v8, v9, vcc
	v_sqrt_f32_e32 v9, v8
	s_waitcnt lgkmcnt(0)
	v_add_f32_e32 v10, v14, v10
	v_add_u32_e32 v11, -1, v9
	v_fma_f32 v12, -v11, v9, v8
	v_mul_f32_e32 v10, v13, v10
	v_cmp_ge_f32_e64 s[2:3], 0, v12
	v_mul_f32_e32 v12, 0x4f800000, v10
	v_cmp_gt_f32_e64 s[0:1], s0, v10
	v_add_u32_e32 v14, 1, v9
	v_fma_f32 v13, -v14, v9, v8
	v_cndmask_b32_e64 v10, v10, v12, s[0:1]
	v_sqrt_f32_e32 v12, v10
	v_cmp_lt_f32_e64 s[6:7], 0, v13
	v_add_u32_e32 v13, -1, v12
	v_fma_f32 v15, -v13, v12, v10
	v_cmp_ge_f32_e64 s[4:5], 0, v15
	v_add_u32_e32 v15, 1, v12
	v_fma_f32 v17, -v15, v12, v10
	v_cmp_lt_f32_e64 s[10:11], 0, v17
	v_lshl_or_b32 v17, v20, 6, v21
	v_mul_lo_u32 v17, v17, s21
	v_add3_u32 v155, s57, v17, v16
	v_mul_lo_u32 v16, v7, s59
	v_readfirstlane_b32 s21, v4
	v_add3_u32 v157, s57, v16, v18
	s_cmpk_lt_i32 s21, 0x100
	s_waitcnt vmcnt(1)
	ds_write_b128 v155, v[146:149]
	s_waitcnt vmcnt(0)
	ds_write_b128 v157, v[150:153] offset:10240
	s_waitcnt lgkmcnt(0)
	s_barrier
	s_cbranch_scc1 .LBB0_607
	s_setprio 1

.LBB0_609:
	global_load_dwordx4 v[146:149], v[160:161], off
	global_load_dwordx4 v[150:153], v[162:163], off
	v_lshl_add_u64 v[160:161], v[160:161], 0, s[54:55]
	v_lshl_add_u64 v[162:163], v[162:163], 0, s[88:89]
	ds_read_b128 v[164:167], v175 offset:0
	ds_read_b128 v[168:171], v175 offset:32
	ds_read_b128 v[226:229], v174 offset:10240
	ds_read_b128 v[234:237], v174 offset:14848
	ds_read_b128 v[230:233], v174 offset:10272
	ds_read_b128 v[238:241], v174 offset:14880
	v_mov_b32_e32 v184, 0
	v_mov_b32_e32 v185, 0
	v_mov_b32_e32 v186, 0
	v_mov_b32_e32 v187, 0
	v_mov_b32_e32 v188, 0
	v_mov_b32_e32 v189, 0
	v_mov_b32_e32 v190, 0
	v_mov_b32_e32 v191, 0
	v_mov_b32_e32 v200, 0
	v_mov_b32_e32 v201, 0
	v_mov_b32_e32 v202, 0
	v_mov_b32_e32 v203, 0
	s_waitcnt lgkmcnt(5)
	v_mfma_f32_32x32x16_bf16 v[96:111], v[164:167], v[130:133], v[64:79]
	s_waitcnt lgkmcnt(4)
	v_mfma_f32_32x32x16_bf16 v[96:111], v[168:171], v[134:137], v[96:111]
	ds_read_b128 v[164:167], v175 offset:5120
	ds_read_b128 v[168:171], v175 offset:5152
	s_waitcnt vmcnt(1)
	ds_write_b128 v155, v[146:149] offset:19456
	s_waitcnt vmcnt(0)
	ds_write_b128 v157, v[150:153] offset:29696
	s_mov_b32 s2, 0
	s_waitcnt lgkmcnt(0)
	s_barrier
.Lat_loop:
	global_load_dwordx4 v[146:149], v[160:161], off
	global_load_dwordx4 v[150:153], v[162:163], off
	v_lshl_add_u64 v[160:161], v[160:161], 0, s[54:55]
	v_lshl_add_u64 v[162:163], v[162:163], 0, s[88:89]
	s_waitcnt lgkmcnt(3)
	v_mfma_f32_32x32x16_bf16 v[112:127], v[164:167], v[138:141], v[80:95]
	v_exp_f32_e32 v96, v96
	v_exp_f32_e32 v97, v97
	v_exp_f32_e32 v98, v98
	s_waitcnt lgkmcnt(2)
	v_mfma_f32_32x32x16_bf16 v[112:127], v[168:171], v[142:145], v[112:127]
	ds_read_b128 v[164:167], v175 offset:2560
	ds_read_b128 v[168:171], v175 offset:2592
	v_exp_f32_e32 v99, v99
	v_exp_f32_e32 v100, v100
	v_exp_f32_e32 v101, v101
	v_mfma_f32_32x32x16_bf16 v[32:47], v[226:229], v[184:187], v[32:47]
	ds_read_b128 v[226:229], v174 offset:10240
	v_exp_f32_e32 v102, v102
	v_exp_f32_e32 v103, v103
	v_exp_f32_e32 v104, v104
	v_mfma_f32_32x32x16_bf16 v[0:15], v[234:237], v[184:187], v[0:15]
	ds_read_b128 v[234:237], v174 offset:14848
	v_exp_f32_e32 v105, v105
	v_exp_f32_e32 v106, v106
	v_exp_f32_e32 v107, v107
	v_mfma_f32_32x32x16_bf16 v[32:47], v[230:233], v[188:191], v[32:47]
	ds_read_b128 v[230:233], v174 offset:10272
	v_exp_f32_e32 v108, v108
	v_exp_f32_e32 v109, v109
	v_exp_f32_e32 v110, v110
	v_exp_f32_e32 v111, v111
	v_mfma_f32_32x32x16_bf16 v[0:15], v[238:241], v[188:191], v[0:15]
	ds_read_b128 v[238:241], v174 offset:14880
	v_pk_add_f32 v[200:201], v[96:97], v[200:201]
	v_cvt_pk_bf16_f32 v176, v96, v97
	v_pk_add_f32 v[200:201], v[98:99], v[200:201]
	v_cvt_pk_bf16_f32 v177, v98, v99
	v_pk_add_f32 v[200:201], v[100:101], v[200:201]
	v_cvt_pk_bf16_f32 v178, v100, v101
	v_pk_add_f32 v[200:201], v[102:103], v[200:201]
	v_cvt_pk_bf16_f32 v179, v102, v103
	v_pk_add_f32 v[200:201], v[104:105], v[200:201]
	v_cvt_pk_bf16_f32 v180, v104, v105
	v_pk_add_f32 v[200:201], v[106:107], v[200:201]
	v_cvt_pk_bf16_f32 v181, v106, v107
	v_pk_add_f32 v[200:201], v[108:109], v[200:201]
	v_cvt_pk_bf16_f32 v182, v108, v109
	v_pk_add_f32 v[200:201], v[110:111], v[200:201]
	v_cvt_pk_bf16_f32 v183, v110, v111
	s_waitcnt lgkmcnt(5)
	v_mfma_f32_32x32x16_bf16 v[96:111], v[164:167], v[130:133], v[64:79]
	v_exp_f32_e32 v112, v112
	v_exp_f32_e32 v113, v113
	v_exp_f32_e32 v114, v114
	s_waitcnt lgkmcnt(4)
	v_mfma_f32_32x32x16_bf16 v[96:111], v[168:171], v[134:137], v[96:111]
	ds_read_b128 v[164:167], v175 offset:7680
	ds_read_b128 v[168:171], v175 offset:7712
	v_exp_f32_e32 v115, v115
	v_exp_f32_e32 v116, v116
	v_exp_f32_e32 v117, v117
	s_waitcnt lgkmcnt(5)
	v_mfma_f32_32x32x16_bf16 v[48:63], v[226:229], v[176:179], v[48:63]
	v_exp_f32_e32 v118, v118
	v_exp_f32_e32 v119, v119
	v_exp_f32_e32 v120, v120
	s_waitcnt lgkmcnt(4)
	v_mfma_f32_32x32x16_bf16 v[16:31], v[234:237], v[176:179], v[16:31]
	v_exp_f32_e32 v121, v121
	v_exp_f32_e32 v122, v122
	v_exp_f32_e32 v123, v123
	s_waitcnt lgkmcnt(3)
	v_mfma_f32_32x32x16_bf16 v[48:63], v[230:233], v[180:183], v[48:63]
	v_exp_f32_e32 v124, v124
	v_exp_f32_e32 v125, v125
	v_exp_f32_e32 v126, v126
	v_exp_f32_e32 v127, v127
	s_waitcnt lgkmcnt(2)
	v_mfma_f32_32x32x16_bf16 v[16:31], v[238:241], v[180:183], v[16:31]
	v_pk_add_f32 v[202:203], v[112:113], v[202:203]
	v_cvt_pk_bf16_f32 v184, v112, v113
	v_pk_add_f32 v[202:203], v[114:115], v[202:203]
	v_cvt_pk_bf16_f32 v185, v114, v115
	v_pk_add_f32 v[202:203], v[116:117], v[202:203]
	v_cvt_pk_bf16_f32 v186, v116, v117
	v_pk_add_f32 v[202:203], v[118:119], v[202:203]
	v_cvt_pk_bf16_f32 v187, v118, v119
	v_pk_add_f32 v[202:203], v[120:121], v[202:203]
	v_cvt_pk_bf16_f32 v188, v120, v121
	v_pk_add_f32 v[202:203], v[122:123], v[202:203]
	v_cvt_pk_bf16_f32 v189, v122, v123
	v_pk_add_f32 v[202:203], v[124:125], v[202:203]
	v_cvt_pk_bf16_f32 v190, v124, v125
	v_pk_add_f32 v[202:203], v[126:127], v[202:203]
	v_cvt_pk_bf16_f32 v191, v126, v127
	s_waitcnt lgkmcnt(1)
	v_mfma_f32_32x32x16_bf16 v[112:127], v[164:167], v[138:141], v[80:95]
	v_exp_f32_e32 v96, v96
	v_exp_f32_e32 v97, v97
	v_exp_f32_e32 v98, v98
	s_waitcnt lgkmcnt(0)
	v_mfma_f32_32x32x16_bf16 v[112:127], v[168:171], v[142:145], v[112:127]
	s_barrier
	ds_read_b128 v[164:167], v175 offset:19456
	ds_read_b128 v[168:171], v175 offset:19488
	v_exp_f32_e32 v99, v99
	v_exp_f32_e32 v100, v100
	v_exp_f32_e32 v101, v101
	v_mfma_f32_32x32x16_bf16 v[32:47], v[226:229], v[184:187], v[32:47]
	ds_read_b128 v[226:229], v174 offset:10304
	v_exp_f32_e32 v102, v102
	v_exp_f32_e32 v103, v103
	v_exp_f32_e32 v104, v104
	v_mfma_f32_32x32x16_bf16 v[0:15], v[234:237], v[184:187], v[0:15]
	ds_read_b128 v[234:237], v174 offset:14912
	v_exp_f32_e32 v105, v105
	v_exp_f32_e32 v106, v106
	v_exp_f32_e32 v107, v107
	v_mfma_f32_32x32x16_bf16 v[32:47], v[230:233], v[188:191], v[32:47]
	ds_read_b128 v[230:233], v174 offset:10336
	v_exp_f32_e32 v108, v108
	v_exp_f32_e32 v109, v109
	v_exp_f32_e32 v110, v110
	v_exp_f32_e32 v111, v111
	v_mfma_f32_32x32x16_bf16 v[0:15], v[238:241], v[188:191], v[0:15]
	ds_read_b128 v[238:241], v174 offset:14944
	v_pk_add_f32 v[200:201], v[96:97], v[200:201]
	v_cvt_pk_bf16_f32 v176, v96, v97
	v_pk_add_f32 v[200:201], v[98:99], v[200:201]
	v_cvt_pk_bf16_f32 v177, v98, v99
	v_pk_add_f32 v[200:201], v[100:101], v[200:201]
	v_cvt_pk_bf16_f32 v178, v100, v101
	v_pk_add_f32 v[200:201], v[102:103], v[200:201]
	v_cvt_pk_bf16_f32 v179, v102, v103
	v_pk_add_f32 v[200:201], v[104:105], v[200:201]
	v_cvt_pk_bf16_f32 v180, v104, v105
	v_pk_add_f32 v[200:201], v[106:107], v[200:201]
	v_cvt_pk_bf16_f32 v181, v106, v107
	v_pk_add_f32 v[200:201], v[108:109], v[200:201]
	v_cvt_pk_bf16_f32 v182, v108, v109
	v_pk_add_f32 v[200:201], v[110:111], v[200:201]
	v_cvt_pk_bf16_f32 v183, v110, v111
	s_waitcnt lgkmcnt(5)
	v_mfma_f32_32x32x16_bf16 v[96:111], v[164:167], v[130:133], v[64:79]
	v_exp_f32_e32 v112, v112
	v_exp_f32_e32 v113, v113
	v_exp_f32_e32 v114, v114
	s_waitcnt lgkmcnt(4)
	v_mfma_f32_32x32x16_bf16 v[96:111], v[168:171], v[134:137], v[96:111]
	ds_read_b128 v[164:167], v175 offset:24576
	ds_read_b128 v[168:171], v175 offset:24608
	v_exp_f32_e32 v115, v115
	v_exp_f32_e32 v116, v116
	v_exp_f32_e32 v117, v117
	s_waitcnt lgkmcnt(5)
	v_mfma_f32_32x32x16_bf16 v[48:63], v[226:229], v[176:179], v[48:63]
	v_exp_f32_e32 v118, v118
	v_exp_f32_e32 v119, v119
	v_exp_f32_e32 v120, v120
	s_waitcnt lgkmcnt(4)
	v_mfma_f32_32x32x16_bf16 v[16:31], v[234:237], v[176:179], v[16:31]
	v_exp_f32_e32 v121, v121
	v_exp_f32_e32 v122, v122
	v_exp_f32_e32 v123, v123
	s_waitcnt lgkmcnt(3)
	v_mfma_f32_32x32x16_bf16 v[48:63], v[230:233], v[180:183], v[48:63]
	v_exp_f32_e32 v124, v124
	v_exp_f32_e32 v125, v125
	v_exp_f32_e32 v126, v126
	v_exp_f32_e32 v127, v127
	s_waitcnt lgkmcnt(2)
	v_mfma_f32_32x32x16_bf16 v[16:31], v[238:241], v[180:183], v[16:31]
	s_waitcnt vmcnt(1)
	ds_write_b128 v155, v[146:149] offset:38912
	s_waitcnt vmcnt(0)
	ds_write_b128 v157, v[150:153] offset:49152
	v_pk_add_f32 v[202:203], v[112:113], v[202:203]
	v_cvt_pk_bf16_f32 v184, v112, v113
	v_pk_add_f32 v[202:203], v[114:115], v[202:203]
	v_cvt_pk_bf16_f32 v185, v114, v115
	v_pk_add_f32 v[202:203], v[116:117], v[202:203]
	v_cvt_pk_bf16_f32 v186, v116, v117
	v_pk_add_f32 v[202:203], v[118:119], v[202:203]
	v_cvt_pk_bf16_f32 v187, v118, v119
	v_pk_add_f32 v[202:203], v[120:121], v[202:203]
	v_cvt_pk_bf16_f32 v188, v120, v121
	v_pk_add_f32 v[202:203], v[122:123], v[202:203]
	v_cvt_pk_bf16_f32 v189, v122, v123
	v_pk_add_f32 v[202:203], v[124:125], v[202:203]
	v_cvt_pk_bf16_f32 v190, v124, v125
	v_pk_add_f32 v[202:203], v[126:127], v[202:203]
	v_cvt_pk_bf16_f32 v191, v126, v127
	s_cmp_eq_u32 s2, 43
	s_cbranch_scc1 .Lat_skip1
	global_load_dwordx4 v[146:149], v[160:161], off
	global_load_dwordx4 v[150:153], v[162:163], off
	v_lshl_add_u64 v[160:161], v[160:161], 0, s[54:55]
	v_lshl_add_u64 v[162:163], v[162:163], 0, s[88:89]
.Lat_skip1:
	s_waitcnt lgkmcnt(3)
	v_mfma_f32_32x32x16_bf16 v[112:127], v[164:167], v[138:141], v[80:95]
	v_exp_f32_e32 v96, v96
	v_exp_f32_e32 v97, v97
	v_exp_f32_e32 v98, v98
	s_waitcnt lgkmcnt(2)
	v_mfma_f32_32x32x16_bf16 v[112:127], v[168:171], v[142:145], v[112:127]
	ds_read_b128 v[164:167], v175 offset:22016
	ds_read_b128 v[168:171], v175 offset:22048
	v_exp_f32_e32 v99, v99
	v_exp_f32_e32 v100, v100
	v_exp_f32_e32 v101, v101
	v_mfma_f32_32x32x16_bf16 v[32:47], v[226:229], v[184:187], v[32:47]
	ds_read_b128 v[226:229], v174 offset:29696
	v_exp_f32_e32 v102, v102
	v_exp_f32_e32 v103, v103
	v_exp_f32_e32 v104, v104
	v_mfma_f32_32x32x16_bf16 v[0:15], v[234:237], v[184:187], v[0:15]
	ds_read_b128 v[234:237], v174 offset:34304
	v_exp_f32_e32 v105, v105
	v_exp_f32_e32 v106, v106
	v_exp_f32_e32 v107, v107
	v_mfma_f32_32x32x16_bf16 v[32:47], v[230:233], v[188:191], v[32:47]
	ds_read_b128 v[230:233], v174 offset:29728
	v_exp_f32_e32 v108, v108
	v_exp_f32_e32 v109, v109
	v_exp_f32_e32 v110, v110
	v_exp_f32_e32 v111, v111
	v_mfma_f32_32x32x16_bf16 v[0:15], v[238:241], v[188:191], v[0:15]
	ds_read_b128 v[238:241], v174 offset:34336
	v_pk_add_f32 v[200:201], v[96:97], v[200:201]
	v_cvt_pk_bf16_f32 v176, v96, v97
	v_pk_add_f32 v[200:201], v[98:99], v[200:201]
	v_cvt_pk_bf16_f32 v177, v98, v99
	v_pk_add_f32 v[200:201], v[100:101], v[200:201]
	v_cvt_pk_bf16_f32 v178, v100, v101
	v_pk_add_f32 v[200:201], v[102:103], v[200:201]
	v_cvt_pk_bf16_f32 v179, v102, v103
	v_pk_add_f32 v[200:201], v[104:105], v[200:201]
	v_cvt_pk_bf16_f32 v180, v104, v105
	v_pk_add_f32 v[200:201], v[106:107], v[200:201]
	v_cvt_pk_bf16_f32 v181, v106, v107
	v_pk_add_f32 v[200:201], v[108:109], v[200:201]
	v_cvt_pk_bf16_f32 v182, v108, v109
	v_pk_add_f32 v[200:201], v[110:111], v[200:201]
	v_cvt_pk_bf16_f32 v183, v110, v111
	s_waitcnt lgkmcnt(5)
	v_mfma_f32_32x32x16_bf16 v[96:111], v[164:167], v[130:133], v[64:79]
	v_exp_f32_e32 v112, v112
	v_exp_f32_e32 v113, v113
	v_exp_f32_e32 v114, v114
	s_waitcnt lgkmcnt(4)
	v_mfma_f32_32x32x16_bf16 v[96:111], v[168:171], v[134:137], v[96:111]
	ds_read_b128 v[164:167], v175 offset:27136
	ds_read_b128 v[168:171], v175 offset:27168
	v_exp_f32_e32 v115, v115
	v_exp_f32_e32 v116, v116
	v_exp_f32_e32 v117, v117
	s_waitcnt lgkmcnt(5)
	v_mfma_f32_32x32x16_bf16 v[48:63], v[226:229], v[176:179], v[48:63]
	v_exp_f32_e32 v118, v118
	v_exp_f32_e32 v119, v119
	v_exp_f32_e32 v120, v120
	s_waitcnt lgkmcnt(4)
	v_mfma_f32_32x32x16_bf16 v[16:31], v[234:237], v[176:179], v[16:31]
	v_exp_f32_e32 v121, v121
	v_exp_f32_e32 v122, v122
	v_exp_f32_e32 v123, v123
	s_waitcnt lgkmcnt(3)
	v_mfma_f32_32x32x16_bf16 v[48:63], v[230:233], v[180:183], v[48:63]
	v_exp_f32_e32 v124, v124
	v_exp_f32_e32 v125, v125
	v_exp_f32_e32 v126, v126
	v_exp_f32_e32 v127, v127
	s_waitcnt lgkmcnt(2)
	v_mfma_f32_32x32x16_bf16 v[16:31], v[238:241], v[180:183], v[16:31]
	v_pk_add_f32 v[202:203], v[112:113], v[202:203]
	v_cvt_pk_bf16_f32 v184, v112, v113
	v_pk_add_f32 v[202:203], v[114:115], v[202:203]
	v_cvt_pk_bf16_f32 v185, v114, v115
	v_pk_add_f32 v[202:203], v[116:117], v[202:203]
	v_cvt_pk_bf16_f32 v186, v116, v117
	v_pk_add_f32 v[202:203], v[118:119], v[202:203]
	v_cvt_pk_bf16_f32 v187, v118, v119
	v_pk_add_f32 v[202:203], v[120:121], v[202:203]
	v_cvt_pk_bf16_f32 v188, v120, v121
	v_pk_add_f32 v[202:203], v[122:123], v[202:203]
	v_cvt_pk_bf16_f32 v189, v122, v123
	v_pk_add_f32 v[202:203], v[124:125], v[202:203]
	v_cvt_pk_bf16_f32 v190, v124, v125
	v_pk_add_f32 v[202:203], v[126:127], v[202:203]
	v_cvt_pk_bf16_f32 v191, v126, v127
	s_waitcnt lgkmcnt(1)
	v_mfma_f32_32x32x16_bf16 v[112:127], v[164:167], v[138:141], v[80:95]
	v_exp_f32_e32 v96, v96
	v_exp_f32_e32 v97, v97
	v_exp_f32_e32 v98, v98
	s_waitcnt lgkmcnt(0)
	v_mfma_f32_32x32x16_bf16 v[112:127], v[168:171], v[142:145], v[112:127]
	s_barrier
	ds_read_b128 v[164:167], v175 offset:38912
	ds_read_b128 v[168:171], v175 offset:38944
	v_exp_f32_e32 v99, v99
	v_exp_f32_e32 v100, v100
	v_exp_f32_e32 v101, v101
	v_mfma_f32_32x32x16_bf16 v[32:47], v[226:229], v[184:187], v[32:47]
	ds_read_b128 v[226:229], v174 offset:29760
	v_exp_f32_e32 v102, v102
	v_exp_f32_e32 v103, v103
	v_exp_f32_e32 v104, v104
	v_mfma_f32_32x32x16_bf16 v[0:15], v[234:237], v[184:187], v[0:15]
	ds_read_b128 v[234:237], v174 offset:34368
	v_exp_f32_e32 v105, v105
	v_exp_f32_e32 v106, v106
	v_exp_f32_e32 v107, v107
	v_mfma_f32_32x32x16_bf16 v[32:47], v[230:233], v[188:191], v[32:47]
	ds_read_b128 v[230:233], v174 offset:29792
	v_exp_f32_e32 v108, v108
	v_exp_f32_e32 v109, v109
	v_exp_f32_e32 v110, v110
	v_exp_f32_e32 v111, v111
	v_mfma_f32_32x32x16_bf16 v[0:15], v[238:241], v[188:191], v[0:15]
	ds_read_b128 v[238:241], v174 offset:34400
	v_pk_add_f32 v[200:201], v[96:97], v[200:201]
	v_cvt_pk_bf16_f32 v176, v96, v97
	v_pk_add_f32 v[200:201], v[98:99], v[200:201]
	v_cvt_pk_bf16_f32 v177, v98, v99
	v_pk_add_f32 v[200:201], v[100:101], v[200:201]
	v_cvt_pk_bf16_f32 v178, v100, v101
	v_pk_add_f32 v[200:201], v[102:103], v[200:201]
	v_cvt_pk_bf16_f32 v179, v102, v103
	v_pk_add_f32 v[200:201], v[104:105], v[200:201]
	v_cvt_pk_bf16_f32 v180, v104, v105
	v_pk_add_f32 v[200:201], v[106:107], v[200:201]
	v_cvt_pk_bf16_f32 v181, v106, v107
	v_pk_add_f32 v[200:201], v[108:109], v[200:201]
	v_cvt_pk_bf16_f32 v182, v108, v109
	v_pk_add_f32 v[200:201], v[110:111], v[200:201]
	v_cvt_pk_bf16_f32 v183, v110, v111
	s_waitcnt lgkmcnt(5)
	v_mfma_f32_32x32x16_bf16 v[96:111], v[164:167], v[130:133], v[64:79]
	v_exp_f32_e32 v112, v112
	v_exp_f32_e32 v113, v113
	v_exp_f32_e32 v114, v114
	s_waitcnt lgkmcnt(4)
	v_mfma_f32_32x32x16_bf16 v[96:111], v[168:171], v[134:137], v[96:111]
	ds_read_b128 v[164:167], v175 offset:44032
	ds_read_b128 v[168:171], v175 offset:44064
	v_exp_f32_e32 v115, v115
	v_exp_f32_e32 v116, v116
	v_exp_f32_e32 v117, v117
	s_waitcnt lgkmcnt(5)
	v_mfma_f32_32x32x16_bf16 v[48:63], v[226:229], v[176:179], v[48:63]
	v_exp_f32_e32 v118, v118
	v_exp_f32_e32 v119, v119
	v_exp_f32_e32 v120, v120
	s_waitcnt lgkmcnt(4)
	v_mfma_f32_32x32x16_bf16 v[16:31], v[234:237], v[176:179], v[16:31]
	v_exp_f32_e32 v121, v121
	v_exp_f32_e32 v122, v122
	v_exp_f32_e32 v123, v123
	s_waitcnt lgkmcnt(3)
	v_mfma_f32_32x32x16_bf16 v[48:63], v[230:233], v[180:183], v[48:63]
	v_exp_f32_e32 v124, v124
	v_exp_f32_e32 v125, v125
	v_exp_f32_e32 v126, v126
	v_exp_f32_e32 v127, v127
	s_waitcnt lgkmcnt(2)
	v_mfma_f32_32x32x16_bf16 v[16:31], v[238:241], v[180:183], v[16:31]
	s_waitcnt vmcnt(1)
	ds_write_b128 v155, v[146:149] offset:0
	s_waitcnt vmcnt(0)
	ds_write_b128 v157, v[150:153] offset:10240
	v_pk_add_f32 v[202:203], v[112:113], v[202:203]
	v_cvt_pk_bf16_f32 v184, v112, v113
	v_pk_add_f32 v[202:203], v[114:115], v[202:203]
	v_cvt_pk_bf16_f32 v185, v114, v115
	v_pk_add_f32 v[202:203], v[116:117], v[202:203]
	v_cvt_pk_bf16_f32 v186, v116, v117
	v_pk_add_f32 v[202:203], v[118:119], v[202:203]
	v_cvt_pk_bf16_f32 v187, v118, v119
	v_pk_add_f32 v[202:203], v[120:121], v[202:203]
	v_cvt_pk_bf16_f32 v188, v120, v121
	v_pk_add_f32 v[202:203], v[122:123], v[202:203]
	v_cvt_pk_bf16_f32 v189, v122, v123
	v_pk_add_f32 v[202:203], v[124:125], v[202:203]
	v_cvt_pk_bf16_f32 v190, v124, v125
	v_pk_add_f32 v[202:203], v[126:127], v[202:203]
	v_cvt_pk_bf16_f32 v191, v126, v127
	s_cmp_eq_u32 s2, 43
	s_cbranch_scc1 .Lat_skip2
	global_load_dwordx4 v[146:149], v[160:161], off
	global_load_dwordx4 v[150:153], v[162:163], off
	v_lshl_add_u64 v[160:161], v[160:161], 0, s[54:55]
	v_lshl_add_u64 v[162:163], v[162:163], 0, s[88:89]
.Lat_skip2:
	s_waitcnt lgkmcnt(3)
	v_mfma_f32_32x32x16_bf16 v[112:127], v[164:167], v[138:141], v[80:95]
	v_exp_f32_e32 v96, v96
	v_exp_f32_e32 v97, v97
	v_exp_f32_e32 v98, v98
	s_waitcnt lgkmcnt(2)
	v_mfma_f32_32x32x16_bf16 v[112:127], v[168:171], v[142:145], v[112:127]
	ds_read_b128 v[164:167], v175 offset:41472
	ds_read_b128 v[168:171], v175 offset:41504
	v_exp_f32_e32 v99, v99
	v_exp_f32_e32 v100, v100
	v_exp_f32_e32 v101, v101
	v_mfma_f32_32x32x16_bf16 v[32:47], v[226:229], v[184:187], v[32:47]
	ds_read_b128 v[226:229], v174 offset:49152
	v_exp_f32_e32 v102, v102
	v_exp_f32_e32 v103, v103
	v_exp_f32_e32 v104, v104
	v_mfma_f32_32x32x16_bf16 v[0:15], v[234:237], v[184:187], v[0:15]
	ds_read_b128 v[234:237], v174 offset:53760
	v_exp_f32_e32 v105, v105
	v_exp_f32_e32 v106, v106
	v_exp_f32_e32 v107, v107
	v_mfma_f32_32x32x16_bf16 v[32:47], v[230:233], v[188:191], v[32:47]
	ds_read_b128 v[230:233], v174 offset:49184
	v_exp_f32_e32 v108, v108
	v_exp_f32_e32 v109, v109
	v_exp_f32_e32 v110, v110
	v_exp_f32_e32 v111, v111
	v_mfma_f32_32x32x16_bf16 v[0:15], v[238:241], v[188:191], v[0:15]
	ds_read_b128 v[238:241], v174 offset:53792
	v_pk_add_f32 v[200:201], v[96:97], v[200:201]
	v_cvt_pk_bf16_f32 v176, v96, v97
	v_pk_add_f32 v[200:201], v[98:99], v[200:201]
	v_cvt_pk_bf16_f32 v177, v98, v99
	v_pk_add_f32 v[200:201], v[100:101], v[200:201]
	v_cvt_pk_bf16_f32 v178, v100, v101
	v_pk_add_f32 v[200:201], v[102:103], v[200:201]
	v_cvt_pk_bf16_f32 v179, v102, v103
	v_pk_add_f32 v[200:201], v[104:105], v[200:201]
	v_cvt_pk_bf16_f32 v180, v104, v105
	v_pk_add_f32 v[200:201], v[106:107], v[200:201]
	v_cvt_pk_bf16_f32 v181, v106, v107
	v_pk_add_f32 v[200:201], v[108:109], v[200:201]
	v_cvt_pk_bf16_f32 v182, v108, v109
	v_pk_add_f32 v[200:201], v[110:111], v[200:201]
	v_cvt_pk_bf16_f32 v183, v110, v111
	s_waitcnt lgkmcnt(5)
	v_mfma_f32_32x32x16_bf16 v[96:111], v[164:167], v[130:133], v[64:79]
	v_exp_f32_e32 v112, v112
	v_exp_f32_e32 v113, v113
	v_exp_f32_e32 v114, v114
	s_waitcnt lgkmcnt(4)
	v_mfma_f32_32x32x16_bf16 v[96:111], v[168:171], v[134:137], v[96:111]
	ds_read_b128 v[164:167], v175 offset:46592
	ds_read_b128 v[168:171], v175 offset:46624
	v_exp_f32_e32 v115, v115
	v_exp_f32_e32 v116, v116
	v_exp_f32_e32 v117, v117
	s_waitcnt lgkmcnt(5)
	v_mfma_f32_32x32x16_bf16 v[48:63], v[226:229], v[176:179], v[48:63]
	v_exp_f32_e32 v118, v118
	v_exp_f32_e32 v119, v119
	v_exp_f32_e32 v120, v120
	s_waitcnt lgkmcnt(4)
	v_mfma_f32_32x32x16_bf16 v[16:31], v[234:237], v[176:179], v[16:31]
	v_exp_f32_e32 v121, v121
	v_exp_f32_e32 v122, v122
	v_exp_f32_e32 v123, v123
	s_waitcnt lgkmcnt(3)
	v_mfma_f32_32x32x16_bf16 v[48:63], v[230:233], v[180:183], v[48:63]
	v_exp_f32_e32 v124, v124
	v_exp_f32_e32 v125, v125
	v_exp_f32_e32 v126, v126
	v_exp_f32_e32 v127, v127
	s_waitcnt lgkmcnt(2)
	v_mfma_f32_32x32x16_bf16 v[16:31], v[238:241], v[180:183], v[16:31]
	v_pk_add_f32 v[202:203], v[112:113], v[202:203]
	v_cvt_pk_bf16_f32 v184, v112, v113
	v_pk_add_f32 v[202:203], v[114:115], v[202:203]
	v_cvt_pk_bf16_f32 v185, v114, v115
	v_pk_add_f32 v[202:203], v[116:117], v[202:203]
	v_cvt_pk_bf16_f32 v186, v116, v117
	v_pk_add_f32 v[202:203], v[118:119], v[202:203]
	v_cvt_pk_bf16_f32 v187, v118, v119
	v_pk_add_f32 v[202:203], v[120:121], v[202:203]
	v_cvt_pk_bf16_f32 v188, v120, v121
	v_pk_add_f32 v[202:203], v[122:123], v[202:203]
	v_cvt_pk_bf16_f32 v189, v122, v123
	v_pk_add_f32 v[202:203], v[124:125], v[202:203]
	v_cvt_pk_bf16_f32 v190, v124, v125
	v_pk_add_f32 v[202:203], v[126:127], v[202:203]
	v_cvt_pk_bf16_f32 v191, v126, v127
	s_waitcnt lgkmcnt(1)
	v_mfma_f32_32x32x16_bf16 v[112:127], v[164:167], v[138:141], v[80:95]
	v_exp_f32_e32 v96, v96
	v_exp_f32_e32 v97, v97
	v_exp_f32_e32 v98, v98
	s_waitcnt lgkmcnt(0)
	v_mfma_f32_32x32x16_bf16 v[112:127], v[168:171], v[142:145], v[112:127]
	s_barrier
	ds_read_b128 v[164:167], v175 offset:0
	ds_read_b128 v[168:171], v175 offset:32
	v_exp_f32_e32 v99, v99
	v_exp_f32_e32 v100, v100
	v_exp_f32_e32 v101, v101
	v_mfma_f32_32x32x16_bf16 v[32:47], v[226:229], v[184:187], v[32:47]
	ds_read_b128 v[226:229], v174 offset:49216
	v_exp_f32_e32 v102, v102
	v_exp_f32_e32 v103, v103
	v_exp_f32_e32 v104, v104
	v_mfma_f32_32x32x16_bf16 v[0:15], v[234:237], v[184:187], v[0:15]
	ds_read_b128 v[234:237], v174 offset:53824
	v_exp_f32_e32 v105, v105
	v_exp_f32_e32 v106, v106
	v_exp_f32_e32 v107, v107
	v_mfma_f32_32x32x16_bf16 v[32:47], v[230:233], v[188:191], v[32:47]
	ds_read_b128 v[230:233], v174 offset:49248
	v_exp_f32_e32 v108, v108
	v_exp_f32_e32 v109, v109
	v_exp_f32_e32 v110, v110
	v_exp_f32_e32 v111, v111
	v_mfma_f32_32x32x16_bf16 v[0:15], v[238:241], v[188:191], v[0:15]
	ds_read_b128 v[238:241], v174 offset:53856
	v_pk_add_f32 v[200:201], v[96:97], v[200:201]
	v_cvt_pk_bf16_f32 v176, v96, v97
	v_pk_add_f32 v[200:201], v[98:99], v[200:201]
	v_cvt_pk_bf16_f32 v177, v98, v99
	v_pk_add_f32 v[200:201], v[100:101], v[200:201]
	v_cvt_pk_bf16_f32 v178, v100, v101
	v_pk_add_f32 v[200:201], v[102:103], v[200:201]
	v_cvt_pk_bf16_f32 v179, v102, v103
	v_pk_add_f32 v[200:201], v[104:105], v[200:201]
	v_cvt_pk_bf16_f32 v180, v104, v105
	v_pk_add_f32 v[200:201], v[106:107], v[200:201]
	v_cvt_pk_bf16_f32 v181, v106, v107
	v_pk_add_f32 v[200:201], v[108:109], v[200:201]
	v_cvt_pk_bf16_f32 v182, v108, v109
	v_pk_add_f32 v[200:201], v[110:111], v[200:201]
	v_cvt_pk_bf16_f32 v183, v110, v111
	s_waitcnt lgkmcnt(5)
	v_mfma_f32_32x32x16_bf16 v[96:111], v[164:167], v[130:133], v[64:79]
	v_exp_f32_e32 v112, v112
	v_exp_f32_e32 v113, v113
	v_exp_f32_e32 v114, v114
	s_waitcnt lgkmcnt(4)
	v_mfma_f32_32x32x16_bf16 v[96:111], v[168:171], v[134:137], v[96:111]
	ds_read_b128 v[164:167], v175 offset:5120
	ds_read_b128 v[168:171], v175 offset:5152
	v_exp_f32_e32 v115, v115
	v_exp_f32_e32 v116, v116
	v_exp_f32_e32 v117, v117
	s_waitcnt lgkmcnt(5)
	v_mfma_f32_32x32x16_bf16 v[48:63], v[226:229], v[176:179], v[48:63]
	v_exp_f32_e32 v118, v118
	v_exp_f32_e32 v119, v119
	v_exp_f32_e32 v120, v120
	s_waitcnt lgkmcnt(4)
	v_mfma_f32_32x32x16_bf16 v[16:31], v[234:237], v[176:179], v[16:31]
	v_exp_f32_e32 v121, v121
	v_exp_f32_e32 v122, v122
	v_exp_f32_e32 v123, v123
	s_waitcnt lgkmcnt(3)
	v_mfma_f32_32x32x16_bf16 v[48:63], v[230:233], v[180:183], v[48:63]
	v_exp_f32_e32 v124, v124
	v_exp_f32_e32 v125, v125
	v_exp_f32_e32 v126, v126
	v_exp_f32_e32 v127, v127
	s_waitcnt lgkmcnt(2)
	v_mfma_f32_32x32x16_bf16 v[16:31], v[238:241], v[180:183], v[16:31]
	s_waitcnt vmcnt(1)
	ds_write_b128 v155, v[146:149] offset:19456
	s_waitcnt vmcnt(0)
	ds_write_b128 v157, v[150:153] offset:29696
	v_pk_add_f32 v[202:203], v[112:113], v[202:203]
	v_cvt_pk_bf16_f32 v184, v112, v113
	v_pk_add_f32 v[202:203], v[114:115], v[202:203]
	v_cvt_pk_bf16_f32 v185, v114, v115
	v_pk_add_f32 v[202:203], v[116:117], v[202:203]
	v_cvt_pk_bf16_f32 v186, v116, v117
	v_pk_add_f32 v[202:203], v[118:119], v[202:203]
	v_cvt_pk_bf16_f32 v187, v118, v119
	v_pk_add_f32 v[202:203], v[120:121], v[202:203]
	v_cvt_pk_bf16_f32 v188, v120, v121
	v_pk_add_f32 v[202:203], v[122:123], v[202:203]
	v_cvt_pk_bf16_f32 v189, v122, v123
	v_pk_add_f32 v[202:203], v[124:125], v[202:203]
	v_cvt_pk_bf16_f32 v190, v124, v125
	v_pk_add_f32 v[202:203], v[126:127], v[202:203]
	v_cvt_pk_bf16_f32 v191, v126, v127
	s_add_i32 s2, s2, 1
	s_cmp_lg_u32 s2, 44
	s_cbranch_scc1 .Lat_loop
	v_mfma_f32_32x32x16_bf16 v[32:47], v[226:229], v[184:187], v[32:47]
	v_mfma_f32_32x32x16_bf16 v[0:15], v[234:237], v[184:187], v[0:15]
	v_mfma_f32_32x32x16_bf16 v[32:47], v[230:233], v[188:191], v[32:47]
	v_mfma_f32_32x32x16_bf16 v[0:15], v[238:241], v[188:191], v[0:15]
	s_waitcnt lgkmcnt(0)
	v_add_f32_e32 v158, v200, v201
	v_add_f32_e32 v159, v202, v203
	s_branch .LBB0_604
